# nt hint also on the E-phase idle-workgroup conversion loads (w_in of the next layer), shift-image task loads left cached
# baseline (speedup 1.0000x reference)
.LBB0_1521:
	s_mul_hi_i32 s0, s14, 0x22b63cbf
	s_lshr_b32 s1, s0, 31
	s_ashr_i32 s0, s0, 10
	s_add_i32 s0, s0, s1
	s_mul_i32 s1, s0, 0xffffe280
	s_add_i32 s8, s14, s1
	s_ashr_i32 s1, s0, 31
	s_mul_i32 s3, s0, 0x1d80000
	v_readlane_b32 s4, v251, 32
	s_mul_hi_i32 s2, s0, 0x1d80000
	s_add_u32 s15, s4, s3
	v_readlane_b32 s3, v251, 33
	s_addc_u32 s18, s3, s2
	s_cmpk_gt_i32 s8, 0x8ff
	s_mov_b64 s[2:3], -1
	s_cbranch_scc0 .LBB0_1539
	s_cmpk_gt_u32 s8, 0x9ff
	s_cbranch_scc0 .LBB0_1536
	s_cmpk_gt_u32 s8, 0xaff
	s_cbranch_scc0 .LBB0_1533
	s_cmpk_gt_u32 s8, 0xcff
	s_cbranch_scc0 .LBB0_1530
	s_cmpk_gt_u32 s8, 0x17ff
	s_cbranch_scc0 .LBB0_1527
	s_mul_i32 s2, s0, 0xffffc500
	s_add_i32 s2, s11, s2
	s_addk_i32 s2, 0xe200
	v_readlane_b32 s24, v254, 54
	s_and_b32 s3, s2, 0x7fffffc0
	s_and_b32 s2, s10, 0x3e0
	s_mul_i32 s5, s0, 0xb00000
	v_readlane_b32 s26, v254, 56
	s_mul_hi_i32 s4, s0, 0xb00000
	v_readlane_b32 s27, v254, 57
	s_add_u32 s5, s26, s5
	s_addc_u32 s9, s27, s4
	s_lshl_b32 s4, s2, 2
	v_add_u32_e32 v6, s3, v1
	s_add_u32 s4, s5, s4
	s_addc_u32 s5, s9, 0
	v_lshlrev_b32_e32 v14, 2, v2
	v_ashrrev_i32_e32 v7, 31, v6
	v_lshl_add_u64 v[12:13], s[4:5], 0, v[14:15]
	v_lshlrev_b64 v[6:7], 12, v[6:7]
	v_lshl_add_u64 v[6:7], v[12:13], 0, v[6:7]
	s_movk_i32 s4, 0x2000
	v_add_co_u32_e32 v12, vcc, s4, v6
	s_movk_i32 s4, 0x4000
	s_nop 0
	v_addc_co_u32_e32 v13, vcc, 0, v7, vcc
	global_load_dword v14, v[6:7], off nt
	global_load_dword v16, v[12:13], off nt
	v_add_co_u32_e32 v12, vcc, s4, v6
	s_movk_i32 s4, 0x6000
	s_nop 0
	v_addc_co_u32_e32 v13, vcc, 0, v7, vcc
	global_load_dword v17, v[12:13], off nt
	v_add_co_u32_e32 v12, vcc, s4, v6
	s_mov_b32 s4, 0xa000
	s_nop 0
	v_addc_co_u32_e32 v13, vcc, 0, v7, vcc
	global_load_dword v18, v[12:13], off nt
	v_add_co_u32_e32 v12, vcc, s66, v6
	s_lshl_b32 s3, s3, 1
	s_nop 0
	v_addc_co_u32_e32 v13, vcc, 0, v7, vcc
	global_load_dword v19, v[12:13], off nt
	v_add_co_u32_e32 v12, vcc, s4, v6
	s_mov_b32 s4, 0xc000
	s_nop 0
	v_addc_co_u32_e32 v13, vcc, 0, v7, vcc
	global_load_dword v20, v[12:13], off nt
	v_add_co_u32_e32 v12, vcc, s4, v6
	s_mov_b32 s4, 0xe000
	s_nop 0
	v_addc_co_u32_e32 v13, vcc, 0, v7, vcc
	global_load_dword v21, v[12:13], off nt
	v_add_co_u32_e32 v12, vcc, s4, v6
	s_mov_b32 s4, 0x12000
	s_nop 0
	v_addc_co_u32_e32 v13, vcc, 0, v7, vcc
	global_load_dword v22, v[12:13], off nt
	v_add_co_u32_e32 v12, vcc, s67, v6
	v_readlane_b32 s25, v254, 55
	s_nop 0
	v_addc_co_u32_e32 v13, vcc, 0, v7, vcc
	global_load_dword v23, v[12:13], off nt
	v_add_co_u32_e32 v12, vcc, s4, v6
	s_mov_b32 s4, 0x14000
	s_nop 0
	v_addc_co_u32_e32 v13, vcc, 0, v7, vcc
	global_load_dword v24, v[12:13], off nt
	v_add_co_u32_e32 v12, vcc, s4, v6
	s_mov_b32 s4, 0x16000
	s_nop 0
	v_addc_co_u32_e32 v13, vcc, 0, v7, vcc
	global_load_dword v25, v[12:13], off nt
	v_add_co_u32_e32 v12, vcc, s4, v6
	s_mov_b32 s4, 0x1a000
	s_nop 0
	v_addc_co_u32_e32 v13, vcc, 0, v7, vcc
	global_load_dword v26, v[12:13], off nt
	v_add_co_u32_e32 v12, vcc, s68, v6
	s_nop 1
	v_addc_co_u32_e32 v13, vcc, 0, v7, vcc
	global_load_dword v27, v[12:13], off nt
	v_add_co_u32_e32 v12, vcc, s4, v6
	s_mov_b32 s4, 0x1c000
	s_nop 0
	v_addc_co_u32_e32 v13, vcc, 0, v7, vcc
	global_load_dword v28, v[12:13], off nt
	v_add_co_u32_e32 v12, vcc, s4, v6
	s_mov_b32 s4, 0x1e000
	s_nop 0
	v_addc_co_u32_e32 v13, vcc, 0, v7, vcc
	global_load_dword v29, v[12:13], off nt
	v_add_co_u32_e32 v12, vcc, s4, v6
	s_mov_b32 s4, 0x20000
	s_nop 0
	v_addc_co_u32_e32 v13, vcc, 0, v7, vcc
	global_load_dword v30, v[12:13], off nt
	v_add_co_u32_e32 v12, vcc, s4, v6
	s_mov_b32 s4, 0x22000
	s_nop 0
	v_addc_co_u32_e32 v13, vcc, 0, v7, vcc
	global_load_dword v31, v[12:13], off nt
	v_add_co_u32_e32 v12, vcc, s4, v6
	s_mov_b32 s4, 0x24000
	s_nop 0
	v_addc_co_u32_e32 v13, vcc, 0, v7, vcc
	global_load_dword v32, v[12:13], off nt
	v_add_co_u32_e32 v12, vcc, s4, v6
	s_mov_b32 s4, 0x26000
	s_nop 0
	v_addc_co_u32_e32 v13, vcc, 0, v7, vcc
	global_load_dword v33, v[12:13], off nt
	v_add_co_u32_e32 v12, vcc, s4, v6
	s_mov_b32 s4, 0x28000
	s_nop 0
	v_addc_co_u32_e32 v13, vcc, 0, v7, vcc
	global_load_dword v34, v[12:13], off nt
	v_add_co_u32_e32 v12, vcc, s4, v6
	s_mov_b32 s4, 0x2a000
	s_nop 0
	v_addc_co_u32_e32 v13, vcc, 0, v7, vcc
	global_load_dword v35, v[12:13], off nt
	v_add_co_u32_e32 v12, vcc, s4, v6
	s_mov_b32 s4, 0x2c000
	s_nop 0
	v_addc_co_u32_e32 v13, vcc, 0, v7, vcc
	global_load_dword v36, v[12:13], off nt
	v_add_co_u32_e32 v12, vcc, s4, v6
	s_mov_b32 s4, 0x2e000
	s_nop 0
	v_addc_co_u32_e32 v13, vcc, 0, v7, vcc
	global_load_dword v37, v[12:13], off nt
	v_add_co_u32_e32 v12, vcc, s4, v6
	s_mov_b32 s4, 0x30000
	s_nop 0
	v_addc_co_u32_e32 v13, vcc, 0, v7, vcc
	global_load_dword v38, v[12:13], off nt
	v_add_co_u32_e32 v12, vcc, s4, v6
	s_mov_b32 s4, 0x32000
	s_nop 0
	v_addc_co_u32_e32 v13, vcc, 0, v7, vcc
	global_load_dword v39, v[12:13], off nt
	v_add_co_u32_e32 v12, vcc, s4, v6
	s_mov_b32 s4, 0x34000
	s_nop 0
	v_addc_co_u32_e32 v13, vcc, 0, v7, vcc
	global_load_dword v40, v[12:13], off nt
	v_add_co_u32_e32 v12, vcc, s4, v6
	s_mov_b32 s4, 0x36000
	s_nop 0
	v_addc_co_u32_e32 v13, vcc, 0, v7, vcc
	global_load_dword v41, v[12:13], off nt
	v_add_co_u32_e32 v12, vcc, s4, v6
	s_mov_b32 s4, 0x38000
	s_nop 0
	v_addc_co_u32_e32 v13, vcc, 0, v7, vcc
	global_load_dword v42, v[12:13], off nt
	v_add_co_u32_e32 v12, vcc, s4, v6
	s_mov_b32 s4, 0x3a000
	s_nop 0
	v_addc_co_u32_e32 v13, vcc, 0, v7, vcc
	global_load_dword v43, v[12:13], off nt
	v_add_co_u32_e32 v12, vcc, s4, v6
	s_mov_b32 s4, 0x3c000
	s_nop 0
	v_addc_co_u32_e32 v13, vcc, 0, v7, vcc
	global_load_dword v44, v[12:13], off nt
	v_add_co_u32_e32 v12, vcc, s4, v6
	s_mov_b32 s4, 0x3e000
	s_nop 0
	v_addc_co_u32_e32 v13, vcc, 0, v7, vcc
	v_add_co_u32_e32 v6, vcc, s4, v6
	global_load_dword v12, v[12:13], off nt
	s_nop 0
	v_addc_co_u32_e32 v7, vcc, 0, v7, vcc
	global_load_dword v6, v[6:7], off nt
	v_add_u32_e32 v7, 0x400, v3
	s_waitcnt vmcnt(30)
	ds_write2_b32 v3, v14, v16 offset1:66
	s_waitcnt vmcnt(28)
	ds_write2_b32 v3, v17, v18 offset0:132 offset1:198
	s_waitcnt vmcnt(26)
	ds_write2_b32 v7, v19, v20 offset0:8 offset1:74
	s_waitcnt vmcnt(24)
	ds_write2_b32 v7, v21, v22 offset0:140 offset1:206
	v_add_u32_e32 v7, 0x800, v3
	s_waitcnt vmcnt(22)
	ds_write2_b32 v7, v23, v24 offset0:16 offset1:82
	s_waitcnt vmcnt(20)
	ds_write2_b32 v7, v25, v26 offset0:148 offset1:214
	v_add_u32_e32 v7, 0xc00, v3
	s_waitcnt vmcnt(18)
	ds_write2_b32 v7, v27, v28 offset0:24 offset1:90
	s_waitcnt vmcnt(16)
	ds_write2_b32 v7, v29, v30 offset0:156 offset1:222
	v_add_u32_e32 v7, 0x1000, v3
	s_waitcnt vmcnt(14)
	ds_write2_b32 v7, v31, v32 offset0:32 offset1:98
	s_waitcnt vmcnt(12)
	ds_write2_b32 v7, v33, v34 offset0:164 offset1:230
	v_add_u32_e32 v7, 0x1400, v3
	s_waitcnt vmcnt(10)
	ds_write2_b32 v7, v35, v36 offset0:40 offset1:106
	s_waitcnt vmcnt(8)
	ds_write2_b32 v7, v37, v38 offset0:172 offset1:238
	v_add_u32_e32 v7, 0x1800, v3
	s_waitcnt vmcnt(6)
	ds_write2_b32 v7, v39, v40 offset0:48 offset1:114
	s_waitcnt vmcnt(4)
	ds_write2_b32 v7, v41, v42 offset0:180 offset1:246
	v_add_u32_e32 v7, 0x1c00, v3
	s_waitcnt vmcnt(2)
	ds_write2_b32 v7, v43, v44 offset0:56 offset1:122
	s_waitcnt vmcnt(0)
	ds_write2_b32 v7, v12, v6 offset0:188 offset1:254
	s_waitcnt lgkmcnt(0)
	ds_read2_b32 v[12:13], v8 offset0:33 offset1:41
	ds_read2_b32 v[20:21], v8 offset1:8
	s_add_u32 s4, s15, s3
	s_addc_u32 s5, s18, 0
	v_lshlrev_b32_e32 v14, 1, v4
	ds_read2_b32 v[22:23], v8 offset0:66 offset1:74
	ds_read2_b32 v[24:25], v8 offset0:99 offset1:107
	v_lshl_add_u64 v[6:7], s[4:5], 0, v[14:15]
	s_waitcnt lgkmcnt(2)
	v_bfe_u32 v14, v20, 16, 1
	s_movk_i32 s3, 0x7fff
	v_add3_u32 v14, v20, v14, s3
	v_bfe_u32 v16, v12, 16, 1
	v_lshrrev_b32_e32 v14, 16, v14
	v_add3_u32 v12, v12, v16, s3
	ds_read2_b32 v[26:27], v8 offset0:132 offset1:140
	ds_read2_b32 v[28:29], v8 offset0:165 offset1:173
	v_and_or_b32 v16, v12, s69, v14
	s_waitcnt lgkmcnt(3)
	v_bfe_u32 v12, v22, 16, 1
	v_add3_u32 v12, v22, v12, s3
	s_waitcnt lgkmcnt(2)
	v_bfe_u32 v14, v24, 16, 1
	v_lshrrev_b32_e32 v12, 16, v12
	v_add3_u32 v14, v24, v14, s3
	ds_read2_b32 v[30:31], v8 offset0:198 offset1:206
	ds_read2_b32 v[32:33], v8 offset0:231 offset1:239
	v_and_or_b32 v17, v14, s69, v12
	s_waitcnt lgkmcnt(3)
	v_bfe_u32 v12, v26, 16, 1
	v_add3_u32 v12, v26, v12, s3
	s_waitcnt lgkmcnt(2)
	v_bfe_u32 v14, v28, 16, 1
	v_lshrrev_b32_e32 v12, 16, v12
	v_add3_u32 v14, v28, v14, s3
	v_and_or_b32 v18, v14, s69, v12
	s_waitcnt lgkmcnt(1)
	v_bfe_u32 v12, v30, 16, 1
	v_add3_u32 v12, v30, v12, s3
	s_waitcnt lgkmcnt(0)
	v_bfe_u32 v14, v32, 16, 1
	s_mov_b64 s[4:5], 0x1800000
	v_lshrrev_b32_e32 v12, 16, v12
	v_add3_u32 v14, v32, v14, s3
	v_lshl_add_u64 v[6:7], v[6:7], 0, s[4:5]
	v_and_or_b32 v19, v14, s69, v12
	v_add_u32_e32 v12, s2, v5
	v_mad_i64_i32 v[34:35], s[4:5], v12, s73, v[6:7]
	v_bfe_u32 v12, v21, 16, 1
	v_add3_u32 v12, v21, v12, s3
	v_bfe_u32 v14, v13, 16, 1
	v_lshrrev_b32_e32 v12, 16, v12
	v_add3_u32 v13, v13, v14, s3
	global_store_dwordx4 v[34:35], v[16:19], off
	s_nop 1
	v_and_or_b32 v16, v13, s69, v12
	v_bfe_u32 v12, v23, 16, 1
	v_add3_u32 v12, v23, v12, s3
	v_bfe_u32 v13, v25, 16, 1
	v_lshrrev_b32_e32 v12, 16, v12
	v_add3_u32 v13, v25, v13, s3
	v_and_or_b32 v17, v13, s69, v12
	v_bfe_u32 v12, v27, 16, 1
	v_add3_u32 v12, v27, v12, s3
	v_bfe_u32 v13, v29, 16, 1
	v_lshrrev_b32_e32 v12, 16, v12
	v_add3_u32 v13, v29, v13, s3
	v_and_or_b32 v18, v13, s69, v12
	v_bfe_u32 v12, v31, 16, 1
	v_add3_u32 v12, v31, v12, s3
	v_bfe_u32 v13, v33, 16, 1
	v_lshrrev_b32_e32 v12, 16, v12
	v_add3_u32 v13, v33, v13, s3
	v_and_or_b32 v19, v13, s69, v12
	v_add_u32_e32 v12, s2, v9
	v_mad_i64_i32 v[12:13], s[4:5], v12, s73, v[6:7]
	global_store_dwordx4 v[12:13], v[16:19], off
	ds_read2_b32 v[12:13], v8 offset0:49 offset1:57
	ds_read2_b32 v[20:21], v8 offset0:16 offset1:24
	ds_read2_b32 v[22:23], v8 offset0:82 offset1:90
	ds_read2_b32 v[24:25], v8 offset0:115 offset1:123
	ds_read2_b32 v[26:27], v8 offset0:148 offset1:156
	ds_read2_b32 v[28:29], v8 offset0:181 offset1:189
	ds_read2_b32 v[30:31], v8 offset0:214 offset1:222
	ds_read2_b32 v[32:33], v8 offset0:247 offset1:255
	s_waitcnt lgkmcnt(7)
	v_bfe_u32 v16, v12, 16, 1
	s_waitcnt lgkmcnt(6)
	v_bfe_u32 v14, v20, 16, 1
	v_add3_u32 v14, v20, v14, s3
	v_lshrrev_b32_e32 v14, 16, v14
	v_add3_u32 v12, v12, v16, s3
	v_and_or_b32 v16, v12, s69, v14
	s_waitcnt lgkmcnt(5)
	v_bfe_u32 v12, v22, 16, 1
	v_add3_u32 v12, v22, v12, s3
	s_waitcnt lgkmcnt(4)
	v_bfe_u32 v14, v24, 16, 1
	v_lshrrev_b32_e32 v12, 16, v12
	v_add3_u32 v14, v24, v14, s3
	v_and_or_b32 v17, v14, s69, v12
	s_waitcnt lgkmcnt(3)
	v_bfe_u32 v12, v26, 16, 1
	v_add3_u32 v12, v26, v12, s3
	s_waitcnt lgkmcnt(2)
	v_bfe_u32 v14, v28, 16, 1
	v_lshrrev_b32_e32 v12, 16, v12
	v_add3_u32 v14, v28, v14, s3
	v_and_or_b32 v18, v14, s69, v12
	s_waitcnt lgkmcnt(1)
	v_bfe_u32 v12, v30, 16, 1
	v_add3_u32 v12, v30, v12, s3
	s_waitcnt lgkmcnt(0)
	v_bfe_u32 v14, v32, 16, 1
	v_lshrrev_b32_e32 v12, 16, v12
	v_add3_u32 v14, v32, v14, s3
	v_and_or_b32 v19, v14, s69, v12
	v_add_u32_e32 v12, s2, v10
	v_mad_i64_i32 v[34:35], s[4:5], v12, s73, v[6:7]
	v_bfe_u32 v12, v21, 16, 1
	v_add3_u32 v12, v21, v12, s3
	v_bfe_u32 v14, v13, 16, 1
	v_lshrrev_b32_e32 v12, 16, v12
	v_add3_u32 v13, v13, v14, s3
	global_store_dwordx4 v[34:35], v[16:19], off
	s_nop 1
	v_and_or_b32 v16, v13, s69, v12
	v_bfe_u32 v12, v23, 16, 1
	v_add3_u32 v12, v23, v12, s3
	v_bfe_u32 v13, v25, 16, 1
	v_lshrrev_b32_e32 v12, 16, v12
	v_add3_u32 v13, v25, v13, s3
	v_and_or_b32 v17, v13, s69, v12
	v_bfe_u32 v12, v27, 16, 1
	v_add3_u32 v12, v27, v12, s3
	v_bfe_u32 v13, v29, 16, 1
	v_lshrrev_b32_e32 v12, 16, v12
	v_add3_u32 v13, v29, v13, s3
	v_and_or_b32 v18, v13, s69, v12
	v_bfe_u32 v12, v31, 16, 1
	v_add3_u32 v12, v31, v12, s3
	v_bfe_u32 v13, v33, 16, 1
	v_lshrrev_b32_e32 v12, 16, v12
	v_add3_u32 v13, v33, v13, s3
	v_and_or_b32 v19, v13, s69, v12
	v_add_u32_e32 v12, s2, v11
	v_mad_i64_i32 v[6:7], s[2:3], v12, s73, v[6:7]
	global_store_dwordx4 v[6:7], v[16:19], off
	s_waitcnt lgkmcnt(0)
	s_mov_b64 s[2:3], 0
.LBB0_1527:
	s_andn2_b64 vcc, exec, s[2:3]
	s_cbranch_vccnz .LBB0_1529
	s_add_i32 s2, s8, 0xf300
	s_and_b32 s3, s2, 0xffff
	s_mul_i32 s3, s3, 0xba2f
	s_lshr_b32 s3, s3, 23
	s_mul_i32 s4, s3, 0xb0
	s_sub_i32 s2, s2, s4
	s_lshl_b32 s4, s2, 5
	v_readlane_b32 s40, v254, 31
	s_and_b32 s5, s4, 0xffe0
	s_mul_i32 s12, s0, 0x1600000
	v_readlane_b32 s44, v254, 35
	s_mul_hi_i32 s9, s0, 0x1600000
	v_readlane_b32 s45, v254, 36
	s_add_u32 s12, s44, s12
	s_addc_u32 s9, s45, s9
	s_and_b32 s2, s2, 0xffff
	s_cmpk_gt_u32 s2, 0x57
	s_cselect_b32 s2, 0xfffff500, 0
	s_cselect_b32 s13, 0x80, 0
	s_add_i32 s2, s2, s5
	s_lshl_b32 s2, s2, 1
	s_and_b32 s4, s4, 0x60
	s_and_b32 s2, s2, 0x7fffff00
	s_or_b32 s4, s4, s13
	s_or_b32 s2, s4, s2
	s_lshl_b32 s4, s5, 2
	s_add_u32 s4, s12, s4
	s_addc_u32 s5, s9, 0
	v_lshlrev_b32_e32 v14, 2, v2
	v_lshl_add_u32 v16, s3, 6, v1
	v_lshl_add_u64 v[6:7], s[4:5], 0, v[14:15]
	s_movk_i32 s9, 0x5800
	v_mad_i64_i32 v[12:13], s[4:5], v16, s9, v[6:7]
	global_load_dword v14, v[12:13], off nt
	v_add_u32_e32 v12, 2, v16
	v_mad_i64_i32 v[12:13], s[4:5], v12, s9, v[6:7]
	global_load_dword v17, v[12:13], off nt
	v_add_u32_e32 v12, 4, v16
	v_mad_i64_i32 v[12:13], s[4:5], v12, s9, v[6:7]
	global_load_dword v18, v[12:13], off nt
	v_add_u32_e32 v12, 6, v16
	v_mad_i64_i32 v[12:13], s[4:5], v12, s9, v[6:7]
	global_load_dword v19, v[12:13], off nt
	v_add_u32_e32 v12, 8, v16
	v_mad_i64_i32 v[12:13], s[4:5], v12, s9, v[6:7]
	global_load_dword v20, v[12:13], off nt
	v_add_u32_e32 v12, 10, v16
	v_mad_i64_i32 v[12:13], s[4:5], v12, s9, v[6:7]
	global_load_dword v21, v[12:13], off nt
	v_add_u32_e32 v12, 12, v16
	v_mad_i64_i32 v[12:13], s[4:5], v12, s9, v[6:7]
	global_load_dword v22, v[12:13], off nt
	v_add_u32_e32 v12, 14, v16
	v_mad_i64_i32 v[12:13], s[4:5], v12, s9, v[6:7]
	global_load_dword v23, v[12:13], off nt
	v_add_u32_e32 v12, 16, v16
	v_mad_i64_i32 v[12:13], s[4:5], v12, s9, v[6:7]
	global_load_dword v24, v[12:13], off nt
	v_add_u32_e32 v12, 18, v16
	v_mad_i64_i32 v[12:13], s[4:5], v12, s9, v[6:7]
	global_load_dword v25, v[12:13], off nt
	v_add_u32_e32 v12, 20, v16
	v_mad_i64_i32 v[12:13], s[4:5], v12, s9, v[6:7]
	global_load_dword v26, v[12:13], off nt
	v_add_u32_e32 v12, 22, v16
	v_mad_i64_i32 v[12:13], s[4:5], v12, s9, v[6:7]
	global_load_dword v27, v[12:13], off nt
	v_add_u32_e32 v12, 24, v16
	v_mad_i64_i32 v[12:13], s[4:5], v12, s9, v[6:7]
	global_load_dword v28, v[12:13], off nt
	v_add_u32_e32 v12, 26, v16
	v_mad_i64_i32 v[12:13], s[4:5], v12, s9, v[6:7]
	global_load_dword v29, v[12:13], off nt
	v_add_u32_e32 v12, 28, v16
	v_mad_i64_i32 v[12:13], s[4:5], v12, s9, v[6:7]
	global_load_dword v30, v[12:13], off nt
	v_add_u32_e32 v12, 30, v16
	v_mad_i64_i32 v[12:13], s[4:5], v12, s9, v[6:7]
	global_load_dword v31, v[12:13], off nt
	v_add_u32_e32 v12, 32, v16
	v_mad_i64_i32 v[12:13], s[4:5], v12, s9, v[6:7]
	global_load_dword v32, v[12:13], off nt
	v_add_u32_e32 v12, 34, v16
	v_mad_i64_i32 v[12:13], s[4:5], v12, s9, v[6:7]
	global_load_dword v33, v[12:13], off nt
	v_add_u32_e32 v12, 36, v16
	v_mad_i64_i32 v[12:13], s[4:5], v12, s9, v[6:7]
	global_load_dword v34, v[12:13], off nt
	v_add_u32_e32 v12, 38, v16
	v_mad_i64_i32 v[12:13], s[4:5], v12, s9, v[6:7]
	global_load_dword v35, v[12:13], off nt
	v_add_u32_e32 v12, 40, v16
	v_mad_i64_i32 v[12:13], s[4:5], v12, s9, v[6:7]
	global_load_dword v36, v[12:13], off nt
	v_add_u32_e32 v12, 42, v16
	v_mad_i64_i32 v[12:13], s[4:5], v12, s9, v[6:7]
	global_load_dword v37, v[12:13], off nt
	v_add_u32_e32 v12, 44, v16
	v_mad_i64_i32 v[12:13], s[4:5], v12, s9, v[6:7]
	global_load_dword v38, v[12:13], off nt
	v_add_u32_e32 v12, 46, v16
	v_mad_i64_i32 v[12:13], s[4:5], v12, s9, v[6:7]
	global_load_dword v39, v[12:13], off nt
	v_add_u32_e32 v12, 48, v16
	v_mad_i64_i32 v[12:13], s[4:5], v12, s9, v[6:7]
	global_load_dword v40, v[12:13], off nt
	v_add_u32_e32 v12, 50, v16
	v_mad_i64_i32 v[12:13], s[4:5], v12, s9, v[6:7]
	global_load_dword v41, v[12:13], off nt
	v_add_u32_e32 v12, 52, v16
	v_mad_i64_i32 v[12:13], s[4:5], v12, s9, v[6:7]
	global_load_dword v42, v[12:13], off nt
	v_add_u32_e32 v12, 54, v16
	v_mad_i64_i32 v[12:13], s[4:5], v12, s9, v[6:7]
	global_load_dword v43, v[12:13], off nt
	v_add_u32_e32 v12, 56, v16
	v_mad_i64_i32 v[12:13], s[4:5], v12, s9, v[6:7]
	global_load_dword v44, v[12:13], off nt
	v_add_u32_e32 v12, 58, v16
	v_mad_i64_i32 v[12:13], s[4:5], v12, s9, v[6:7]
	global_load_dword v45, v[12:13], off nt
	v_add_u32_e32 v12, 60, v16
	v_mad_i64_i32 v[12:13], s[4:5], v12, s9, v[6:7]
	global_load_dword v12, v[12:13], off nt
	v_add_u32_e32 v13, 62, v16
	v_mad_i64_i32 v[6:7], s[4:5], v13, s9, v[6:7]
	global_load_dword v6, v[6:7], off nt
	v_add_u32_e32 v7, 0x400, v3
	s_waitcnt vmcnt(30)
	ds_write2_b32 v3, v14, v17 offset1:66
	s_waitcnt vmcnt(28)
	ds_write2_b32 v3, v18, v19 offset0:132 offset1:198
	s_waitcnt vmcnt(26)
	ds_write2_b32 v7, v20, v21 offset0:8 offset1:74
	s_waitcnt vmcnt(24)
	ds_write2_b32 v7, v22, v23 offset0:140 offset1:206
	v_add_u32_e32 v7, 0x800, v3
	s_waitcnt vmcnt(22)
	ds_write2_b32 v7, v24, v25 offset0:16 offset1:82
	s_waitcnt vmcnt(20)
	ds_write2_b32 v7, v26, v27 offset0:148 offset1:214
	v_add_u32_e32 v7, 0xc00, v3
	s_waitcnt vmcnt(18)
	ds_write2_b32 v7, v28, v29 offset0:24 offset1:90
	s_waitcnt vmcnt(16)
	ds_write2_b32 v7, v30, v31 offset0:156 offset1:222
	v_add_u32_e32 v7, 0x1000, v3
	s_waitcnt vmcnt(14)
	ds_write2_b32 v7, v32, v33 offset0:32 offset1:98
	s_waitcnt vmcnt(12)
	ds_write2_b32 v7, v34, v35 offset0:164 offset1:230
	v_add_u32_e32 v7, 0x1400, v3
	s_waitcnt vmcnt(10)
	ds_write2_b32 v7, v36, v37 offset0:40 offset1:106
	s_waitcnt vmcnt(8)
	ds_write2_b32 v7, v38, v39 offset0:172 offset1:238
	v_add_u32_e32 v7, 0x1800, v3
	s_waitcnt vmcnt(6)
	ds_write2_b32 v7, v40, v41 offset0:48 offset1:114
	s_waitcnt vmcnt(4)
	ds_write2_b32 v7, v42, v43 offset0:180 offset1:246
	v_add_u32_e32 v7, 0x1c00, v3
	s_waitcnt vmcnt(2)
	ds_write2_b32 v7, v44, v45 offset0:56 offset1:122
	s_waitcnt vmcnt(0)
	ds_write2_b32 v7, v12, v6 offset0:188 offset1:254
	s_waitcnt lgkmcnt(0)
	ds_read2_b32 v[12:13], v8 offset0:33 offset1:41
	ds_read2_b32 v[20:21], v8 offset1:8
	s_lshl_b32 s3, s3, 7
	s_add_u32 s4, s15, s3
	s_addc_u32 s5, s18, 0
	v_lshlrev_b32_e32 v14, 1, v4
	ds_read2_b32 v[22:23], v8 offset0:66 offset1:74
	ds_read2_b32 v[24:25], v8 offset0:99 offset1:107
	v_lshl_add_u64 v[6:7], s[4:5], 0, v[14:15]
	s_waitcnt lgkmcnt(2)
	v_bfe_u32 v14, v20, 16, 1
	s_movk_i32 s3, 0x7fff
	v_add3_u32 v14, v20, v14, s3
	v_bfe_u32 v16, v12, 16, 1
	v_lshrrev_b32_e32 v14, 16, v14
	v_add3_u32 v12, v12, v16, s3
	ds_read2_b32 v[26:27], v8 offset0:132 offset1:140
	ds_read2_b32 v[28:29], v8 offset0:165 offset1:173
	v_and_or_b32 v16, v12, s69, v14
	s_waitcnt lgkmcnt(3)
	v_bfe_u32 v12, v22, 16, 1
	v_add3_u32 v12, v22, v12, s3
	s_waitcnt lgkmcnt(2)
	v_bfe_u32 v14, v24, 16, 1
	v_lshrrev_b32_e32 v12, 16, v12
	v_add3_u32 v14, v24, v14, s3
	ds_read2_b32 v[30:31], v8 offset0:198 offset1:206
	ds_read2_b32 v[32:33], v8 offset0:231 offset1:239
	v_and_or_b32 v17, v14, s69, v12
	s_waitcnt lgkmcnt(3)
	v_bfe_u32 v12, v26, 16, 1
	v_add3_u32 v12, v26, v12, s3
	s_waitcnt lgkmcnt(2)
	v_bfe_u32 v14, v28, 16, 1
	v_lshrrev_b32_e32 v12, 16, v12
	v_add3_u32 v14, v28, v14, s3
	v_and_or_b32 v18, v14, s69, v12
	s_waitcnt lgkmcnt(1)
	v_bfe_u32 v12, v30, 16, 1
	v_add3_u32 v12, v30, v12, s3
	s_waitcnt lgkmcnt(0)
	v_bfe_u32 v14, v32, 16, 1
	v_lshrrev_b32_e32 v12, 16, v12
	v_add3_u32 v14, v32, v14, s3
	v_add_u32_e32 v34, s2, v5
	s_mov_b64 s[4:5], 0xd00000
	v_and_or_b32 v19, v14, s69, v12
	v_ashrrev_i32_e32 v35, 31, v34
	v_bfe_u32 v12, v21, 16, 1
	v_lshl_add_u64 v[6:7], v[6:7], 0, s[4:5]
	v_lshlrev_b64 v[34:35], 11, v[34:35]
	v_add3_u32 v12, v21, v12, s3
	v_bfe_u32 v14, v13, 16, 1
	v_lshl_add_u64 v[34:35], v[6:7], 0, v[34:35]
	v_lshrrev_b32_e32 v12, 16, v12
	v_add3_u32 v13, v13, v14, s3
	global_store_dwordx4 v[34:35], v[16:19], off
	v_add_u32_e32 v34, s2, v10
	v_ashrrev_i32_e32 v35, 31, v34
	v_and_or_b32 v16, v13, s69, v12
	v_bfe_u32 v12, v23, 16, 1
	v_add3_u32 v12, v23, v12, s3
	v_bfe_u32 v13, v25, 16, 1
	v_lshrrev_b32_e32 v12, 16, v12
	v_add3_u32 v13, v25, v13, s3
	v_and_or_b32 v17, v13, s69, v12
	v_bfe_u32 v12, v27, 16, 1
	v_add3_u32 v12, v27, v12, s3
	v_bfe_u32 v13, v29, 16, 1
	v_lshrrev_b32_e32 v12, 16, v12
	v_add3_u32 v13, v29, v13, s3
	v_and_or_b32 v18, v13, s69, v12
	v_bfe_u32 v12, v31, 16, 1
	v_add3_u32 v12, v31, v12, s3
	v_bfe_u32 v13, v33, 16, 1
	v_lshrrev_b32_e32 v12, 16, v12
	v_add3_u32 v13, v33, v13, s3
	v_and_or_b32 v19, v13, s69, v12
	v_add_u32_e32 v12, s2, v9
	v_ashrrev_i32_e32 v13, 31, v12
	v_lshlrev_b64 v[12:13], 11, v[12:13]
	v_lshl_add_u64 v[12:13], v[6:7], 0, v[12:13]
	global_store_dwordx4 v[12:13], v[16:19], off
	ds_read2_b32 v[12:13], v8 offset0:49 offset1:57
	ds_read2_b32 v[20:21], v8 offset0:16 offset1:24
	ds_read2_b32 v[22:23], v8 offset0:82 offset1:90
	ds_read2_b32 v[24:25], v8 offset0:115 offset1:123
	ds_read2_b32 v[26:27], v8 offset0:148 offset1:156
	ds_read2_b32 v[28:29], v8 offset0:181 offset1:189
	ds_read2_b32 v[30:31], v8 offset0:214 offset1:222
	ds_read2_b32 v[32:33], v8 offset0:247 offset1:255
	s_waitcnt lgkmcnt(7)
	v_bfe_u32 v16, v12, 16, 1
	s_waitcnt lgkmcnt(6)
	v_bfe_u32 v14, v20, 16, 1
	v_add3_u32 v14, v20, v14, s3
	v_lshrrev_b32_e32 v14, 16, v14
	v_add3_u32 v12, v12, v16, s3
	v_and_or_b32 v16, v12, s69, v14
	s_waitcnt lgkmcnt(5)
	v_bfe_u32 v12, v22, 16, 1
	v_add3_u32 v12, v22, v12, s3
	s_waitcnt lgkmcnt(4)
	v_bfe_u32 v14, v24, 16, 1
	v_lshrrev_b32_e32 v12, 16, v12
	v_add3_u32 v14, v24, v14, s3
	v_and_or_b32 v17, v14, s69, v12
	s_waitcnt lgkmcnt(3)
	v_bfe_u32 v12, v26, 16, 1
	v_add3_u32 v12, v26, v12, s3
	s_waitcnt lgkmcnt(2)
	v_bfe_u32 v14, v28, 16, 1
	v_lshrrev_b32_e32 v12, 16, v12
	v_add3_u32 v14, v28, v14, s3
	v_and_or_b32 v18, v14, s69, v12
	s_waitcnt lgkmcnt(1)
	v_bfe_u32 v12, v30, 16, 1
	v_add3_u32 v12, v30, v12, s3
	s_waitcnt lgkmcnt(0)
	v_bfe_u32 v14, v32, 16, 1
	v_lshrrev_b32_e32 v12, 16, v12
	v_add3_u32 v14, v32, v14, s3
	v_and_or_b32 v19, v14, s69, v12
	v_bfe_u32 v12, v21, 16, 1
	v_lshlrev_b64 v[34:35], 11, v[34:35]
	v_add3_u32 v12, v21, v12, s3
	v_bfe_u32 v14, v13, 16, 1
	v_lshl_add_u64 v[34:35], v[6:7], 0, v[34:35]
	v_lshrrev_b32_e32 v12, 16, v12
	v_add3_u32 v13, v13, v14, s3
	global_store_dwordx4 v[34:35], v[16:19], off
	v_readlane_b32 s41, v254, 32
	v_readlane_b32 s42, v254, 33
	v_and_or_b32 v16, v13, s69, v12
	v_bfe_u32 v12, v23, 16, 1
	v_add3_u32 v12, v23, v12, s3
	v_bfe_u32 v13, v25, 16, 1
	v_lshrrev_b32_e32 v12, 16, v12
	v_add3_u32 v13, v25, v13, s3
	v_and_or_b32 v17, v13, s69, v12
	v_bfe_u32 v12, v27, 16, 1
	v_add3_u32 v12, v27, v12, s3
	v_bfe_u32 v13, v29, 16, 1
	v_lshrrev_b32_e32 v12, 16, v12
	v_add3_u32 v13, v29, v13, s3
	v_and_or_b32 v18, v13, s69, v12
	v_bfe_u32 v12, v31, 16, 1
	v_add3_u32 v12, v31, v12, s3
	v_bfe_u32 v13, v33, 16, 1
	v_lshrrev_b32_e32 v12, 16, v12
	v_add3_u32 v13, v33, v13, s3
	v_and_or_b32 v19, v13, s69, v12
	v_add_u32_e32 v12, s2, v11
	v_ashrrev_i32_e32 v13, 31, v12
	v_lshlrev_b64 v[12:13], 11, v[12:13]
	v_lshl_add_u64 v[6:7], v[6:7], 0, v[12:13]
	global_store_dwordx4 v[6:7], v[16:19], off
	s_waitcnt lgkmcnt(0)
	v_readlane_b32 s43, v254, 34
	v_readlane_b32 s46, v254, 37
	v_readlane_b32 s47, v254, 38

.LBB0_1530:
	s_andn2_b64 vcc, exec, s[2:3]
	s_cbranch_vccnz .LBB0_1532
	s_mul_i32 s2, s0, 0xffffc500
	s_add_i32 s2, s11, s2
	s_addk_i32 s2, 0xfc00
	v_readlane_b32 s40, v254, 31
	s_and_b32 s3, s2, 0x7fffffc0
	s_and_b32 s2, s10, 0x3e0
	s_lshl_b64 s[4:5], s[0:1], 22
	v_readlane_b32 s42, v254, 33
	v_readlane_b32 s43, v254, 34
	s_add_u32 s4, s42, s4
	s_addc_u32 s5, s43, s5
	s_lshl_b32 s9, s2, 2
	v_add_u32_e32 v6, s3, v1
	s_add_u32 s4, s4, s9
	s_addc_u32 s5, s5, 0
	v_lshlrev_b32_e32 v14, 2, v2
	v_ashrrev_i32_e32 v7, 31, v6
	v_lshl_add_u64 v[12:13], s[4:5], 0, v[14:15]
	v_lshlrev_b64 v[6:7], 12, v[6:7]
	v_lshl_add_u64 v[6:7], v[12:13], 0, v[6:7]
	s_movk_i32 s4, 0x2000
	v_add_co_u32_e32 v12, vcc, s4, v6
	s_movk_i32 s4, 0x4000
	s_nop 0
	v_addc_co_u32_e32 v13, vcc, 0, v7, vcc
	global_load_dword v14, v[6:7], off nt
	global_load_dword v16, v[12:13], off nt
	v_add_co_u32_e32 v12, vcc, s4, v6
	s_movk_i32 s4, 0x6000
	s_nop 0
	v_addc_co_u32_e32 v13, vcc, 0, v7, vcc
	global_load_dword v17, v[12:13], off nt
	v_add_co_u32_e32 v12, vcc, s4, v6
	s_mov_b32 s4, 0xa000
	s_nop 0
	v_addc_co_u32_e32 v13, vcc, 0, v7, vcc
	global_load_dword v18, v[12:13], off nt
	v_add_co_u32_e32 v12, vcc, s66, v6
	s_lshl_b32 s3, s3, 1
	s_nop 0
	v_addc_co_u32_e32 v13, vcc, 0, v7, vcc
	global_load_dword v19, v[12:13], off nt
	v_add_co_u32_e32 v12, vcc, s4, v6
	s_mov_b32 s4, 0xc000
	s_nop 0
	v_addc_co_u32_e32 v13, vcc, 0, v7, vcc
	global_load_dword v20, v[12:13], off nt
	v_add_co_u32_e32 v12, vcc, s4, v6
	s_mov_b32 s4, 0xe000
	s_nop 0
	v_addc_co_u32_e32 v13, vcc, 0, v7, vcc
	global_load_dword v21, v[12:13], off nt
	v_add_co_u32_e32 v12, vcc, s4, v6
	s_mov_b32 s4, 0x12000
	s_nop 0
	v_addc_co_u32_e32 v13, vcc, 0, v7, vcc
	global_load_dword v22, v[12:13], off nt
	v_add_co_u32_e32 v12, vcc, s67, v6
	v_readlane_b32 s41, v254, 32
	s_nop 0
	v_addc_co_u32_e32 v13, vcc, 0, v7, vcc
	global_load_dword v23, v[12:13], off nt
	v_add_co_u32_e32 v12, vcc, s4, v6
	s_mov_b32 s4, 0x14000
	s_nop 0
	v_addc_co_u32_e32 v13, vcc, 0, v7, vcc
	global_load_dword v24, v[12:13], off nt
	v_add_co_u32_e32 v12, vcc, s4, v6
	s_mov_b32 s4, 0x16000
	s_nop 0
	v_addc_co_u32_e32 v13, vcc, 0, v7, vcc
	global_load_dword v25, v[12:13], off nt
	v_add_co_u32_e32 v12, vcc, s4, v6
	s_mov_b32 s4, 0x1a000
	s_nop 0
	v_addc_co_u32_e32 v13, vcc, 0, v7, vcc
	global_load_dword v26, v[12:13], off nt
	v_add_co_u32_e32 v12, vcc, s68, v6
	v_readlane_b32 s44, v254, 35
	s_nop 0
	v_addc_co_u32_e32 v13, vcc, 0, v7, vcc
	global_load_dword v27, v[12:13], off nt
	v_add_co_u32_e32 v12, vcc, s4, v6
	s_mov_b32 s4, 0x1c000
	s_nop 0
	v_addc_co_u32_e32 v13, vcc, 0, v7, vcc
	global_load_dword v28, v[12:13], off nt
	v_add_co_u32_e32 v12, vcc, s4, v6
	s_mov_b32 s4, 0x1e000
	s_nop 0
	v_addc_co_u32_e32 v13, vcc, 0, v7, vcc
	global_load_dword v29, v[12:13], off nt
	v_add_co_u32_e32 v12, vcc, s4, v6
	s_mov_b32 s4, 0x20000
	s_nop 0
	v_addc_co_u32_e32 v13, vcc, 0, v7, vcc
	global_load_dword v30, v[12:13], off nt
	v_add_co_u32_e32 v12, vcc, s4, v6
	s_mov_b32 s4, 0x22000
	s_nop 0
	v_addc_co_u32_e32 v13, vcc, 0, v7, vcc
	global_load_dword v31, v[12:13], off nt
	v_add_co_u32_e32 v12, vcc, s4, v6
	s_mov_b32 s4, 0x24000
	s_nop 0
	v_addc_co_u32_e32 v13, vcc, 0, v7, vcc
	global_load_dword v32, v[12:13], off nt
	v_add_co_u32_e32 v12, vcc, s4, v6
	s_mov_b32 s4, 0x26000
	s_nop 0
	v_addc_co_u32_e32 v13, vcc, 0, v7, vcc
	global_load_dword v33, v[12:13], off nt
	v_add_co_u32_e32 v12, vcc, s4, v6
	s_mov_b32 s4, 0x28000
	s_nop 0
	v_addc_co_u32_e32 v13, vcc, 0, v7, vcc
	global_load_dword v34, v[12:13], off nt
	v_add_co_u32_e32 v12, vcc, s4, v6
	s_mov_b32 s4, 0x2a000
	s_nop 0
	v_addc_co_u32_e32 v13, vcc, 0, v7, vcc
	global_load_dword v35, v[12:13], off nt
	v_add_co_u32_e32 v12, vcc, s4, v6
	s_mov_b32 s4, 0x2c000
	s_nop 0
	v_addc_co_u32_e32 v13, vcc, 0, v7, vcc
	global_load_dword v36, v[12:13], off nt
	v_add_co_u32_e32 v12, vcc, s4, v6
	s_mov_b32 s4, 0x2e000
	s_nop 0
	v_addc_co_u32_e32 v13, vcc, 0, v7, vcc
	global_load_dword v37, v[12:13], off nt
	v_add_co_u32_e32 v12, vcc, s4, v6
	s_mov_b32 s4, 0x30000
	s_nop 0
	v_addc_co_u32_e32 v13, vcc, 0, v7, vcc
	global_load_dword v38, v[12:13], off nt
	v_add_co_u32_e32 v12, vcc, s4, v6
	s_mov_b32 s4, 0x32000
	s_nop 0
	v_addc_co_u32_e32 v13, vcc, 0, v7, vcc
	global_load_dword v39, v[12:13], off nt
	v_add_co_u32_e32 v12, vcc, s4, v6
	s_mov_b32 s4, 0x34000
	s_nop 0
	v_addc_co_u32_e32 v13, vcc, 0, v7, vcc
	global_load_dword v40, v[12:13], off nt
	v_add_co_u32_e32 v12, vcc, s4, v6
	s_mov_b32 s4, 0x36000
	s_nop 0
	v_addc_co_u32_e32 v13, vcc, 0, v7, vcc
	global_load_dword v41, v[12:13], off nt
	v_add_co_u32_e32 v12, vcc, s4, v6
	s_mov_b32 s4, 0x38000
	s_nop 0
	v_addc_co_u32_e32 v13, vcc, 0, v7, vcc
	global_load_dword v42, v[12:13], off nt
	v_add_co_u32_e32 v12, vcc, s4, v6
	s_mov_b32 s4, 0x3a000
	s_nop 0
	v_addc_co_u32_e32 v13, vcc, 0, v7, vcc
	global_load_dword v43, v[12:13], off nt
	v_add_co_u32_e32 v12, vcc, s4, v6
	s_mov_b32 s4, 0x3c000
	s_nop 0
	v_addc_co_u32_e32 v13, vcc, 0, v7, vcc
	global_load_dword v44, v[12:13], off nt
	v_add_co_u32_e32 v12, vcc, s4, v6
	s_mov_b32 s4, 0x3e000
	s_nop 0
	v_addc_co_u32_e32 v13, vcc, 0, v7, vcc
	v_add_co_u32_e32 v6, vcc, s4, v6
	global_load_dword v12, v[12:13], off nt
	s_nop 0
	v_addc_co_u32_e32 v7, vcc, 0, v7, vcc
	global_load_dword v6, v[6:7], off nt
	v_add_u32_e32 v7, 0x400, v3
	s_waitcnt vmcnt(30)
	ds_write2_b32 v3, v14, v16 offset1:66
	s_waitcnt vmcnt(28)
	ds_write2_b32 v3, v17, v18 offset0:132 offset1:198
	s_waitcnt vmcnt(26)
	ds_write2_b32 v7, v19, v20 offset0:8 offset1:74
	s_waitcnt vmcnt(24)
	ds_write2_b32 v7, v21, v22 offset0:140 offset1:206
	v_add_u32_e32 v7, 0x800, v3
	s_waitcnt vmcnt(22)
	ds_write2_b32 v7, v23, v24 offset0:16 offset1:82
	s_waitcnt vmcnt(20)
	ds_write2_b32 v7, v25, v26 offset0:148 offset1:214
	v_add_u32_e32 v7, 0xc00, v3
	s_waitcnt vmcnt(18)
	ds_write2_b32 v7, v27, v28 offset0:24 offset1:90
	s_waitcnt vmcnt(16)
	ds_write2_b32 v7, v29, v30 offset0:156 offset1:222
	v_add_u32_e32 v7, 0x1000, v3
	s_waitcnt vmcnt(14)
	ds_write2_b32 v7, v31, v32 offset0:32 offset1:98
	s_waitcnt vmcnt(12)
	ds_write2_b32 v7, v33, v34 offset0:164 offset1:230
	v_add_u32_e32 v7, 0x1400, v3
	s_waitcnt vmcnt(10)
	ds_write2_b32 v7, v35, v36 offset0:40 offset1:106
	s_waitcnt vmcnt(8)
	ds_write2_b32 v7, v37, v38 offset0:172 offset1:238
	v_add_u32_e32 v7, 0x1800, v3
	s_waitcnt vmcnt(6)
	ds_write2_b32 v7, v39, v40 offset0:48 offset1:114
	s_waitcnt vmcnt(4)
	ds_write2_b32 v7, v41, v42 offset0:180 offset1:246
	v_add_u32_e32 v7, 0x1c00, v3
	s_waitcnt vmcnt(2)
	ds_write2_b32 v7, v43, v44 offset0:56 offset1:122
	s_waitcnt vmcnt(0)
	ds_write2_b32 v7, v12, v6 offset0:188 offset1:254
	s_waitcnt lgkmcnt(0)
	ds_read2_b32 v[12:13], v8 offset0:33 offset1:41
	ds_read2_b32 v[20:21], v8 offset1:8
	s_add_u32 s4, s15, s3
	s_addc_u32 s5, s18, 0
	v_lshlrev_b32_e32 v14, 1, v4
	ds_read2_b32 v[22:23], v8 offset0:66 offset1:74
	ds_read2_b32 v[24:25], v8 offset0:99 offset1:107
	v_lshl_add_u64 v[6:7], s[4:5], 0, v[14:15]
	s_waitcnt lgkmcnt(2)
	v_bfe_u32 v14, v20, 16, 1
	s_movk_i32 s3, 0x7fff
	v_add3_u32 v14, v20, v14, s3
	v_bfe_u32 v16, v12, 16, 1
	v_lshrrev_b32_e32 v14, 16, v14
	v_add3_u32 v12, v12, v16, s3
	ds_read2_b32 v[26:27], v8 offset0:132 offset1:140
	ds_read2_b32 v[28:29], v8 offset0:165 offset1:173
	v_and_or_b32 v16, v12, s69, v14
	s_waitcnt lgkmcnt(3)
	v_bfe_u32 v12, v22, 16, 1
	v_add3_u32 v12, v22, v12, s3
	s_waitcnt lgkmcnt(2)
	v_bfe_u32 v14, v24, 16, 1
	v_lshrrev_b32_e32 v12, 16, v12
	v_add3_u32 v14, v24, v14, s3
	ds_read2_b32 v[30:31], v8 offset0:198 offset1:206
	ds_read2_b32 v[32:33], v8 offset0:231 offset1:239
	v_and_or_b32 v17, v14, s69, v12
	s_waitcnt lgkmcnt(3)
	v_bfe_u32 v12, v26, 16, 1
	v_add3_u32 v12, v26, v12, s3
	s_waitcnt lgkmcnt(2)
	v_bfe_u32 v14, v28, 16, 1
	v_lshrrev_b32_e32 v12, 16, v12
	v_add3_u32 v14, v28, v14, s3
	v_and_or_b32 v18, v14, s69, v12
	s_waitcnt lgkmcnt(1)
	v_bfe_u32 v12, v30, 16, 1
	v_add3_u32 v12, v30, v12, s3
	s_waitcnt lgkmcnt(0)
	v_bfe_u32 v14, v32, 16, 1
	v_lshrrev_b32_e32 v12, 16, v12
	v_add3_u32 v14, v32, v14, s3
	v_add_u32_e32 v34, s2, v5
	s_mov_b64 s[4:5], 0xb00000
	v_and_or_b32 v19, v14, s69, v12
	v_ashrrev_i32_e32 v35, 31, v34
	v_bfe_u32 v12, v21, 16, 1
	v_lshl_add_u64 v[6:7], v[6:7], 0, s[4:5]
	v_lshlrev_b64 v[34:35], 11, v[34:35]
	v_add3_u32 v12, v21, v12, s3
	v_bfe_u32 v14, v13, 16, 1
	v_lshl_add_u64 v[34:35], v[6:7], 0, v[34:35]
	v_lshrrev_b32_e32 v12, 16, v12
	v_add3_u32 v13, v13, v14, s3
	global_store_dwordx4 v[34:35], v[16:19], off
	v_add_u32_e32 v34, s2, v10
	v_ashrrev_i32_e32 v35, 31, v34
	v_and_or_b32 v16, v13, s69, v12
	v_bfe_u32 v12, v23, 16, 1
	v_add3_u32 v12, v23, v12, s3
	v_bfe_u32 v13, v25, 16, 1
	v_lshrrev_b32_e32 v12, 16, v12
	v_add3_u32 v13, v25, v13, s3
	v_and_or_b32 v17, v13, s69, v12
	v_bfe_u32 v12, v27, 16, 1
	v_add3_u32 v12, v27, v12, s3
	v_bfe_u32 v13, v29, 16, 1
	v_lshrrev_b32_e32 v12, 16, v12
	v_add3_u32 v13, v29, v13, s3
	v_and_or_b32 v18, v13, s69, v12
	v_bfe_u32 v12, v31, 16, 1
	v_add3_u32 v12, v31, v12, s3
	v_bfe_u32 v13, v33, 16, 1
	v_lshrrev_b32_e32 v12, 16, v12
	v_add3_u32 v13, v33, v13, s3
	v_and_or_b32 v19, v13, s69, v12
	v_add_u32_e32 v12, s2, v9
	v_ashrrev_i32_e32 v13, 31, v12
	v_lshlrev_b64 v[12:13], 11, v[12:13]
	v_lshl_add_u64 v[12:13], v[6:7], 0, v[12:13]
	global_store_dwordx4 v[12:13], v[16:19], off
	ds_read2_b32 v[12:13], v8 offset0:49 offset1:57
	ds_read2_b32 v[20:21], v8 offset0:16 offset1:24
	ds_read2_b32 v[22:23], v8 offset0:82 offset1:90
	ds_read2_b32 v[24:25], v8 offset0:115 offset1:123
	ds_read2_b32 v[26:27], v8 offset0:148 offset1:156
	ds_read2_b32 v[28:29], v8 offset0:181 offset1:189
	ds_read2_b32 v[30:31], v8 offset0:214 offset1:222
	ds_read2_b32 v[32:33], v8 offset0:247 offset1:255
	s_waitcnt lgkmcnt(7)
	v_bfe_u32 v16, v12, 16, 1
	s_waitcnt lgkmcnt(6)
	v_bfe_u32 v14, v20, 16, 1
	v_add3_u32 v14, v20, v14, s3
	v_lshrrev_b32_e32 v14, 16, v14
	v_add3_u32 v12, v12, v16, s3
	v_and_or_b32 v16, v12, s69, v14
	s_waitcnt lgkmcnt(5)
	v_bfe_u32 v12, v22, 16, 1
	v_add3_u32 v12, v22, v12, s3
	s_waitcnt lgkmcnt(4)
	v_bfe_u32 v14, v24, 16, 1
	v_lshrrev_b32_e32 v12, 16, v12
	v_add3_u32 v14, v24, v14, s3
	v_and_or_b32 v17, v14, s69, v12
	s_waitcnt lgkmcnt(3)
	v_bfe_u32 v12, v26, 16, 1
	v_add3_u32 v12, v26, v12, s3
	s_waitcnt lgkmcnt(2)
	v_bfe_u32 v14, v28, 16, 1
	v_lshrrev_b32_e32 v12, 16, v12
	v_add3_u32 v14, v28, v14, s3
	v_and_or_b32 v18, v14, s69, v12
	s_waitcnt lgkmcnt(1)
	v_bfe_u32 v12, v30, 16, 1
	v_add3_u32 v12, v30, v12, s3
	s_waitcnt lgkmcnt(0)
	v_bfe_u32 v14, v32, 16, 1
	v_lshrrev_b32_e32 v12, 16, v12
	v_add3_u32 v14, v32, v14, s3
	v_and_or_b32 v19, v14, s69, v12
	v_bfe_u32 v12, v21, 16, 1
	v_lshlrev_b64 v[34:35], 11, v[34:35]
	v_add3_u32 v12, v21, v12, s3
	v_bfe_u32 v14, v13, 16, 1
	v_lshl_add_u64 v[34:35], v[6:7], 0, v[34:35]
	v_lshrrev_b32_e32 v12, 16, v12
	v_add3_u32 v13, v13, v14, s3
	global_store_dwordx4 v[34:35], v[16:19], off
	v_readlane_b32 s45, v254, 36
	v_readlane_b32 s46, v254, 37
	v_and_or_b32 v16, v13, s69, v12
	v_bfe_u32 v12, v23, 16, 1
	v_add3_u32 v12, v23, v12, s3
	v_bfe_u32 v13, v25, 16, 1
	v_lshrrev_b32_e32 v12, 16, v12
	v_add3_u32 v13, v25, v13, s3
	v_and_or_b32 v17, v13, s69, v12
	v_bfe_u32 v12, v27, 16, 1
	v_add3_u32 v12, v27, v12, s3
	v_bfe_u32 v13, v29, 16, 1
	v_lshrrev_b32_e32 v12, 16, v12
	v_add3_u32 v13, v29, v13, s3
	v_and_or_b32 v18, v13, s69, v12
	v_bfe_u32 v12, v31, 16, 1
	v_add3_u32 v12, v31, v12, s3
	v_bfe_u32 v13, v33, 16, 1
	v_lshrrev_b32_e32 v12, 16, v12
	v_add3_u32 v13, v33, v13, s3
	v_and_or_b32 v19, v13, s69, v12
	v_add_u32_e32 v12, s2, v11
	v_ashrrev_i32_e32 v13, 31, v12
	v_lshlrev_b64 v[12:13], 11, v[12:13]
	v_lshl_add_u64 v[6:7], v[6:7], 0, v[12:13]
	global_store_dwordx4 v[6:7], v[16:19], off
	s_waitcnt lgkmcnt(0)
	v_readlane_b32 s47, v254, 38

.LBB0_1533:
	s_andn2_b64 vcc, exec, s[2:3]
	s_cbranch_vccnz .LBB0_1535
	s_mul_i32 s2, s0, 0xffffc500
	s_add_i32 s2, s11, s2
	s_addk_i32 s2, 0xfe00
	s_and_b32 s3, s2, 0x7fffffc0
	s_and_b32 s2, s10, 0x3e0
	s_lshl_b64 s[4:5], s[0:1], 21
	v_readlane_b32 s40, v254, 31
	v_readlane_b32 s41, v254, 32
	s_add_u32 s4, s40, s4
	s_addc_u32 s5, s41, s5
	s_lshl_b32 s9, s2, 2
	v_add_u32_e32 v6, s3, v1
	s_add_u32 s4, s4, s9
	s_addc_u32 s5, s5, 0
	v_lshlrev_b32_e32 v14, 2, v2
	v_ashrrev_i32_e32 v7, 31, v6
	v_lshl_add_u64 v[12:13], s[4:5], 0, v[14:15]
	v_lshlrev_b64 v[6:7], 12, v[6:7]
	v_lshl_add_u64 v[6:7], v[12:13], 0, v[6:7]
	s_movk_i32 s4, 0x2000
	v_add_co_u32_e32 v12, vcc, s4, v6
	s_movk_i32 s4, 0x4000
	s_nop 0
	v_addc_co_u32_e32 v13, vcc, 0, v7, vcc
	global_load_dword v14, v[6:7], off nt
	global_load_dword v16, v[12:13], off nt
	v_add_co_u32_e32 v12, vcc, s4, v6
	s_movk_i32 s4, 0x6000
	s_nop 0
	v_addc_co_u32_e32 v13, vcc, 0, v7, vcc
	global_load_dword v17, v[12:13], off nt
	v_add_co_u32_e32 v12, vcc, s4, v6
	s_mov_b32 s4, 0xa000
	s_nop 0
	v_addc_co_u32_e32 v13, vcc, 0, v7, vcc
	global_load_dword v18, v[12:13], off nt
	v_add_co_u32_e32 v12, vcc, s66, v6
	s_lshl_b32 s3, s3, 1
	s_nop 0
	v_addc_co_u32_e32 v13, vcc, 0, v7, vcc
	global_load_dword v19, v[12:13], off nt
	v_add_co_u32_e32 v12, vcc, s4, v6
	s_mov_b32 s4, 0xc000
	s_nop 0
	v_addc_co_u32_e32 v13, vcc, 0, v7, vcc
	global_load_dword v20, v[12:13], off nt
	v_add_co_u32_e32 v12, vcc, s4, v6
	s_mov_b32 s4, 0xe000
	s_nop 0
	v_addc_co_u32_e32 v13, vcc, 0, v7, vcc
	global_load_dword v21, v[12:13], off nt
	v_add_co_u32_e32 v12, vcc, s4, v6
	s_mov_b32 s4, 0x12000
	s_nop 0
	v_addc_co_u32_e32 v13, vcc, 0, v7, vcc
	global_load_dword v22, v[12:13], off nt
	v_add_co_u32_e32 v12, vcc, s67, v6
	v_readlane_b32 s42, v254, 33
	s_nop 0
	v_addc_co_u32_e32 v13, vcc, 0, v7, vcc
	global_load_dword v23, v[12:13], off nt
	v_add_co_u32_e32 v12, vcc, s4, v6
	s_mov_b32 s4, 0x14000
	s_nop 0
	v_addc_co_u32_e32 v13, vcc, 0, v7, vcc
	global_load_dword v24, v[12:13], off nt
	v_add_co_u32_e32 v12, vcc, s4, v6
	s_mov_b32 s4, 0x16000
	s_nop 0
	v_addc_co_u32_e32 v13, vcc, 0, v7, vcc
	global_load_dword v25, v[12:13], off nt
	v_add_co_u32_e32 v12, vcc, s4, v6
	s_mov_b32 s4, 0x1a000
	s_nop 0
	v_addc_co_u32_e32 v13, vcc, 0, v7, vcc
	global_load_dword v26, v[12:13], off nt
	v_add_co_u32_e32 v12, vcc, s68, v6
	v_readlane_b32 s43, v254, 34
	s_nop 0
	v_addc_co_u32_e32 v13, vcc, 0, v7, vcc
	global_load_dword v27, v[12:13], off nt
	v_add_co_u32_e32 v12, vcc, s4, v6
	s_mov_b32 s4, 0x1c000
	s_nop 0
	v_addc_co_u32_e32 v13, vcc, 0, v7, vcc
	global_load_dword v28, v[12:13], off nt
	v_add_co_u32_e32 v12, vcc, s4, v6
	s_mov_b32 s4, 0x1e000
	s_nop 0
	v_addc_co_u32_e32 v13, vcc, 0, v7, vcc
	global_load_dword v29, v[12:13], off nt
	v_add_co_u32_e32 v12, vcc, s4, v6
	s_mov_b32 s4, 0x20000
	s_nop 0
	v_addc_co_u32_e32 v13, vcc, 0, v7, vcc
	global_load_dword v30, v[12:13], off nt
	v_add_co_u32_e32 v12, vcc, s4, v6
	s_mov_b32 s4, 0x22000
	s_nop 0
	v_addc_co_u32_e32 v13, vcc, 0, v7, vcc
	global_load_dword v31, v[12:13], off nt
	v_add_co_u32_e32 v12, vcc, s4, v6
	s_mov_b32 s4, 0x24000
	s_nop 0
	v_addc_co_u32_e32 v13, vcc, 0, v7, vcc
	global_load_dword v32, v[12:13], off nt
	v_add_co_u32_e32 v12, vcc, s4, v6
	s_mov_b32 s4, 0x26000
	s_nop 0
	v_addc_co_u32_e32 v13, vcc, 0, v7, vcc
	global_load_dword v33, v[12:13], off nt
	v_add_co_u32_e32 v12, vcc, s4, v6
	s_mov_b32 s4, 0x28000
	s_nop 0
	v_addc_co_u32_e32 v13, vcc, 0, v7, vcc
	global_load_dword v34, v[12:13], off nt
	v_add_co_u32_e32 v12, vcc, s4, v6
	s_mov_b32 s4, 0x2a000
	s_nop 0
	v_addc_co_u32_e32 v13, vcc, 0, v7, vcc
	global_load_dword v35, v[12:13], off nt
	v_add_co_u32_e32 v12, vcc, s4, v6
	s_mov_b32 s4, 0x2c000
	s_nop 0
	v_addc_co_u32_e32 v13, vcc, 0, v7, vcc
	global_load_dword v36, v[12:13], off nt
	v_add_co_u32_e32 v12, vcc, s4, v6
	s_mov_b32 s4, 0x2e000
	s_nop 0
	v_addc_co_u32_e32 v13, vcc, 0, v7, vcc
	global_load_dword v37, v[12:13], off nt
	v_add_co_u32_e32 v12, vcc, s4, v6
	s_mov_b32 s4, 0x30000
	s_nop 0
	v_addc_co_u32_e32 v13, vcc, 0, v7, vcc
	global_load_dword v38, v[12:13], off nt
	v_add_co_u32_e32 v12, vcc, s4, v6
	s_mov_b32 s4, 0x32000
	s_nop 0
	v_addc_co_u32_e32 v13, vcc, 0, v7, vcc
	global_load_dword v39, v[12:13], off nt
	v_add_co_u32_e32 v12, vcc, s4, v6
	s_mov_b32 s4, 0x34000
	s_nop 0
	v_addc_co_u32_e32 v13, vcc, 0, v7, vcc
	global_load_dword v40, v[12:13], off nt
	v_add_co_u32_e32 v12, vcc, s4, v6
	s_mov_b32 s4, 0x36000
	s_nop 0
	v_addc_co_u32_e32 v13, vcc, 0, v7, vcc
	global_load_dword v41, v[12:13], off nt
	v_add_co_u32_e32 v12, vcc, s4, v6
	s_mov_b32 s4, 0x38000
	s_nop 0
	v_addc_co_u32_e32 v13, vcc, 0, v7, vcc
	global_load_dword v42, v[12:13], off nt
	v_add_co_u32_e32 v12, vcc, s4, v6
	s_mov_b32 s4, 0x3a000
	s_nop 0
	v_addc_co_u32_e32 v13, vcc, 0, v7, vcc
	global_load_dword v43, v[12:13], off nt
	v_add_co_u32_e32 v12, vcc, s4, v6
	s_mov_b32 s4, 0x3c000
	s_nop 0
	v_addc_co_u32_e32 v13, vcc, 0, v7, vcc
	global_load_dword v44, v[12:13], off nt
	v_add_co_u32_e32 v12, vcc, s4, v6
	s_mov_b32 s4, 0x3e000
	s_nop 0
	v_addc_co_u32_e32 v13, vcc, 0, v7, vcc
	v_add_co_u32_e32 v6, vcc, s4, v6
	global_load_dword v12, v[12:13], off nt
	s_nop 0
	v_addc_co_u32_e32 v7, vcc, 0, v7, vcc
	global_load_dword v6, v[6:7], off nt
	v_add_u32_e32 v7, 0x400, v3
	s_waitcnt vmcnt(30)
	ds_write2_b32 v3, v14, v16 offset1:66
	s_waitcnt vmcnt(28)
	ds_write2_b32 v3, v17, v18 offset0:132 offset1:198
	s_waitcnt vmcnt(26)
	ds_write2_b32 v7, v19, v20 offset0:8 offset1:74
	s_waitcnt vmcnt(24)
	ds_write2_b32 v7, v21, v22 offset0:140 offset1:206
	v_add_u32_e32 v7, 0x800, v3
	s_waitcnt vmcnt(22)
	ds_write2_b32 v7, v23, v24 offset0:16 offset1:82
	s_waitcnt vmcnt(20)
	ds_write2_b32 v7, v25, v26 offset0:148 offset1:214
	v_add_u32_e32 v7, 0xc00, v3
	s_waitcnt vmcnt(18)
	ds_write2_b32 v7, v27, v28 offset0:24 offset1:90
	s_waitcnt vmcnt(16)
	ds_write2_b32 v7, v29, v30 offset0:156 offset1:222
	v_add_u32_e32 v7, 0x1000, v3
	s_waitcnt vmcnt(14)
	ds_write2_b32 v7, v31, v32 offset0:32 offset1:98
	s_waitcnt vmcnt(12)
	ds_write2_b32 v7, v33, v34 offset0:164 offset1:230
	v_add_u32_e32 v7, 0x1400, v3
	s_waitcnt vmcnt(10)
	ds_write2_b32 v7, v35, v36 offset0:40 offset1:106
	s_waitcnt vmcnt(8)
	ds_write2_b32 v7, v37, v38 offset0:172 offset1:238
	v_add_u32_e32 v7, 0x1800, v3
	s_waitcnt vmcnt(6)
	ds_write2_b32 v7, v39, v40 offset0:48 offset1:114
	s_waitcnt vmcnt(4)
	ds_write2_b32 v7, v41, v42 offset0:180 offset1:246
	v_add_u32_e32 v7, 0x1c00, v3
	s_waitcnt vmcnt(2)
	ds_write2_b32 v7, v43, v44 offset0:56 offset1:122
	s_waitcnt vmcnt(0)
	ds_write2_b32 v7, v12, v6 offset0:188 offset1:254
	s_waitcnt lgkmcnt(0)
	ds_read2_b32 v[12:13], v8 offset0:33 offset1:41
	ds_read2_b32 v[20:21], v8 offset1:8
	s_add_u32 s4, s15, s3
	s_addc_u32 s5, s18, 0
	v_lshlrev_b32_e32 v14, 1, v4
	ds_read2_b32 v[22:23], v8 offset0:66 offset1:74
	ds_read2_b32 v[24:25], v8 offset0:99 offset1:107
	v_lshl_add_u64 v[6:7], s[4:5], 0, v[14:15]
	s_waitcnt lgkmcnt(2)
	v_bfe_u32 v14, v20, 16, 1
	s_movk_i32 s3, 0x7fff
	v_add3_u32 v14, v20, v14, s3
	v_bfe_u32 v16, v12, 16, 1
	v_lshrrev_b32_e32 v14, 16, v14
	v_add3_u32 v12, v12, v16, s3
	ds_read2_b32 v[26:27], v8 offset0:132 offset1:140
	ds_read2_b32 v[28:29], v8 offset0:165 offset1:173
	v_and_or_b32 v16, v12, s69, v14
	s_waitcnt lgkmcnt(3)
	v_bfe_u32 v12, v22, 16, 1
	v_add3_u32 v12, v22, v12, s3
	s_waitcnt lgkmcnt(2)
	v_bfe_u32 v14, v24, 16, 1
	v_lshrrev_b32_e32 v12, 16, v12
	v_add3_u32 v14, v24, v14, s3
	ds_read2_b32 v[30:31], v8 offset0:198 offset1:206
	ds_read2_b32 v[32:33], v8 offset0:231 offset1:239
	v_and_or_b32 v17, v14, s69, v12
	s_waitcnt lgkmcnt(3)
	v_bfe_u32 v12, v26, 16, 1
	v_add3_u32 v12, v26, v12, s3
	s_waitcnt lgkmcnt(2)
	v_bfe_u32 v14, v28, 16, 1
	v_lshrrev_b32_e32 v12, 16, v12
	v_add3_u32 v14, v28, v14, s3
	v_and_or_b32 v18, v14, s69, v12
	s_waitcnt lgkmcnt(1)
	v_bfe_u32 v12, v30, 16, 1
	v_add3_u32 v12, v30, v12, s3
	s_waitcnt lgkmcnt(0)
	v_bfe_u32 v14, v32, 16, 1
	v_lshrrev_b32_e32 v12, 16, v12
	v_add3_u32 v14, v32, v14, s3
	v_add_u32_e32 v34, s2, v5
	s_mov_b64 s[4:5], 0x900400
	v_and_or_b32 v19, v14, s69, v12
	v_ashrrev_i32_e32 v35, 31, v34
	v_bfe_u32 v12, v21, 16, 1
	v_lshl_add_u64 v[6:7], v[6:7], 0, s[4:5]
	v_lshlrev_b64 v[34:35], 11, v[34:35]
	v_add3_u32 v12, v21, v12, s3
	v_bfe_u32 v14, v13, 16, 1
	v_lshl_add_u64 v[34:35], v[6:7], 0, v[34:35]
	v_lshrrev_b32_e32 v12, 16, v12
	v_add3_u32 v13, v13, v14, s3
	global_store_dwordx4 v[34:35], v[16:19], off
	v_add_u32_e32 v34, s2, v10
	v_ashrrev_i32_e32 v35, 31, v34
	v_and_or_b32 v16, v13, s69, v12
	v_bfe_u32 v12, v23, 16, 1
	v_add3_u32 v12, v23, v12, s3
	v_bfe_u32 v13, v25, 16, 1
	v_lshrrev_b32_e32 v12, 16, v12
	v_add3_u32 v13, v25, v13, s3
	v_and_or_b32 v17, v13, s69, v12
	v_bfe_u32 v12, v27, 16, 1
	v_add3_u32 v12, v27, v12, s3
	v_bfe_u32 v13, v29, 16, 1
	v_lshrrev_b32_e32 v12, 16, v12
	v_add3_u32 v13, v29, v13, s3
	v_and_or_b32 v18, v13, s69, v12
	v_bfe_u32 v12, v31, 16, 1
	v_add3_u32 v12, v31, v12, s3
	v_bfe_u32 v13, v33, 16, 1
	v_lshrrev_b32_e32 v12, 16, v12
	v_add3_u32 v13, v33, v13, s3
	v_and_or_b32 v19, v13, s69, v12
	v_add_u32_e32 v12, s2, v9
	v_ashrrev_i32_e32 v13, 31, v12
	v_lshlrev_b64 v[12:13], 11, v[12:13]
	v_lshl_add_u64 v[12:13], v[6:7], 0, v[12:13]
	global_store_dwordx4 v[12:13], v[16:19], off
	ds_read2_b32 v[12:13], v8 offset0:49 offset1:57
	ds_read2_b32 v[20:21], v8 offset0:16 offset1:24
	ds_read2_b32 v[22:23], v8 offset0:82 offset1:90
	ds_read2_b32 v[24:25], v8 offset0:115 offset1:123
	ds_read2_b32 v[26:27], v8 offset0:148 offset1:156
	ds_read2_b32 v[28:29], v8 offset0:181 offset1:189
	ds_read2_b32 v[30:31], v8 offset0:214 offset1:222
	ds_read2_b32 v[32:33], v8 offset0:247 offset1:255
	s_waitcnt lgkmcnt(7)
	v_bfe_u32 v16, v12, 16, 1
	s_waitcnt lgkmcnt(6)
	v_bfe_u32 v14, v20, 16, 1
	v_add3_u32 v14, v20, v14, s3
	v_lshrrev_b32_e32 v14, 16, v14
	v_add3_u32 v12, v12, v16, s3
	v_and_or_b32 v16, v12, s69, v14
	s_waitcnt lgkmcnt(5)
	v_bfe_u32 v12, v22, 16, 1
	v_add3_u32 v12, v22, v12, s3
	s_waitcnt lgkmcnt(4)
	v_bfe_u32 v14, v24, 16, 1
	v_lshrrev_b32_e32 v12, 16, v12
	v_add3_u32 v14, v24, v14, s3
	v_and_or_b32 v17, v14, s69, v12
	s_waitcnt lgkmcnt(3)
	v_bfe_u32 v12, v26, 16, 1
	v_add3_u32 v12, v26, v12, s3
	s_waitcnt lgkmcnt(2)
	v_bfe_u32 v14, v28, 16, 1
	v_lshrrev_b32_e32 v12, 16, v12
	v_add3_u32 v14, v28, v14, s3
	v_and_or_b32 v18, v14, s69, v12
	s_waitcnt lgkmcnt(1)
	v_bfe_u32 v12, v30, 16, 1
	v_add3_u32 v12, v30, v12, s3
	s_waitcnt lgkmcnt(0)
	v_bfe_u32 v14, v32, 16, 1
	v_lshrrev_b32_e32 v12, 16, v12
	v_add3_u32 v14, v32, v14, s3
	v_and_or_b32 v19, v14, s69, v12
	v_bfe_u32 v12, v21, 16, 1
	v_lshlrev_b64 v[34:35], 11, v[34:35]
	v_add3_u32 v12, v21, v12, s3
	v_bfe_u32 v14, v13, 16, 1
	v_lshl_add_u64 v[34:35], v[6:7], 0, v[34:35]
	v_lshrrev_b32_e32 v12, 16, v12
	v_add3_u32 v13, v13, v14, s3
	global_store_dwordx4 v[34:35], v[16:19], off
	v_readlane_b32 s44, v254, 35
	v_readlane_b32 s45, v254, 36
	v_and_or_b32 v16, v13, s69, v12
	v_bfe_u32 v12, v23, 16, 1
	v_add3_u32 v12, v23, v12, s3
	v_bfe_u32 v13, v25, 16, 1
	v_lshrrev_b32_e32 v12, 16, v12
	v_add3_u32 v13, v25, v13, s3
	v_and_or_b32 v17, v13, s69, v12
	v_bfe_u32 v12, v27, 16, 1
	v_add3_u32 v12, v27, v12, s3
	v_bfe_u32 v13, v29, 16, 1
	v_lshrrev_b32_e32 v12, 16, v12
	v_add3_u32 v13, v29, v13, s3
	v_and_or_b32 v18, v13, s69, v12
	v_bfe_u32 v12, v31, 16, 1
	v_add3_u32 v12, v31, v12, s3
	v_bfe_u32 v13, v33, 16, 1
	v_lshrrev_b32_e32 v12, 16, v12
	v_add3_u32 v13, v33, v13, s3
	v_and_or_b32 v19, v13, s69, v12
	v_add_u32_e32 v12, s2, v11
	v_ashrrev_i32_e32 v13, 31, v12
	v_lshlrev_b64 v[12:13], 11, v[12:13]
	v_lshl_add_u64 v[6:7], v[6:7], 0, v[12:13]
	global_store_dwordx4 v[6:7], v[16:19], off
	s_waitcnt lgkmcnt(0)
	v_readlane_b32 s46, v254, 37
	v_readlane_b32 s47, v254, 38

.LBB0_1536:
	s_andn2_b64 vcc, exec, s[2:3]
	s_cbranch_vccnz .LBB0_1538
	s_mul_i32 s2, s0, 0xffffc500
	s_add_i32 s2, s11, s2
	v_readlane_b32 s60, v250, 15
	s_and_b32 s3, s2, 0x7fffffc0
	s_and_b32 s2, s10, 0x3e0
	s_lshl_b64 s[4:5], s[0:1], 21
	v_readlane_b32 s74, v250, 29
	v_readlane_b32 s75, v250, 30
	s_add_u32 s1, s74, s4
	s_addc_u32 s5, s75, s5
	s_lshl_b32 s4, s2, 2
	v_add_u32_e32 v6, s3, v1
	s_add_u32 s4, s1, s4
	s_addc_u32 s5, s5, 0
	v_lshlrev_b32_e32 v14, 2, v2
	v_ashrrev_i32_e32 v7, 31, v6
	v_lshl_add_u64 v[12:13], s[4:5], 0, v[14:15]
	v_lshlrev_b64 v[6:7], 12, v[6:7]
	v_lshl_add_u64 v[6:7], v[12:13], 0, v[6:7]
	s_movk_i32 s1, 0x2000
	v_add_co_u32_e32 v12, vcc, s1, v6
	s_movk_i32 s1, 0x4000
	s_nop 0
	v_addc_co_u32_e32 v13, vcc, 0, v7, vcc
	global_load_dword v14, v[6:7], off nt
	global_load_dword v16, v[12:13], off nt
	v_add_co_u32_e32 v12, vcc, s1, v6
	s_movk_i32 s1, 0x6000
	s_nop 0
	v_addc_co_u32_e32 v13, vcc, 0, v7, vcc
	v_readlane_b32 s66, v250, 21
	global_load_dword v17, v[12:13], off nt
	v_add_co_u32_e32 v12, vcc, s1, v6
	s_mov_b32 s66, 0x8000
	s_nop 0
	v_addc_co_u32_e32 v13, vcc, 0, v7, vcc
	global_load_dword v18, v[12:13], off nt
	v_add_co_u32_e32 v12, vcc, s66, v6
	s_mov_b32 s1, 0xa000
	s_nop 0
	v_addc_co_u32_e32 v13, vcc, 0, v7, vcc
	global_load_dword v19, v[12:13], off nt
	v_add_co_u32_e32 v12, vcc, s1, v6
	s_mov_b32 s1, 0xc000
	s_nop 0
	v_addc_co_u32_e32 v13, vcc, 0, v7, vcc
	global_load_dword v20, v[12:13], off nt
	v_add_co_u32_e32 v12, vcc, s1, v6
	s_mov_b32 s1, 0xe000
	s_nop 0
	v_addc_co_u32_e32 v13, vcc, 0, v7, vcc
	v_readlane_b32 s67, v250, 22
	global_load_dword v21, v[12:13], off nt
	v_add_co_u32_e32 v12, vcc, s1, v6
	s_mov_b32 s67, 0x10000
	s_nop 0
	v_addc_co_u32_e32 v13, vcc, 0, v7, vcc
	global_load_dword v22, v[12:13], off nt
	v_add_co_u32_e32 v12, vcc, s67, v6
	s_mov_b32 s1, 0x12000
	s_nop 0
	v_addc_co_u32_e32 v13, vcc, 0, v7, vcc
	global_load_dword v23, v[12:13], off nt
	v_add_co_u32_e32 v12, vcc, s1, v6
	s_mov_b32 s1, 0x14000
	s_nop 0
	v_addc_co_u32_e32 v13, vcc, 0, v7, vcc
	global_load_dword v24, v[12:13], off nt
	v_add_co_u32_e32 v12, vcc, s1, v6
	s_mov_b32 s1, 0x16000
	s_nop 0
	v_addc_co_u32_e32 v13, vcc, 0, v7, vcc
	v_readlane_b32 s68, v250, 23
	global_load_dword v25, v[12:13], off nt
	v_add_co_u32_e32 v12, vcc, s1, v6
	s_mov_b32 s68, 0x18000
	s_nop 0
	v_addc_co_u32_e32 v13, vcc, 0, v7, vcc
	global_load_dword v26, v[12:13], off nt
	v_add_co_u32_e32 v12, vcc, s68, v6
	s_mov_b32 s1, 0x1a000
	s_nop 0
	v_addc_co_u32_e32 v13, vcc, 0, v7, vcc
	global_load_dword v27, v[12:13], off nt
	v_add_co_u32_e32 v12, vcc, s1, v6
	s_mov_b32 s1, 0x1c000
	s_nop 0
	v_addc_co_u32_e32 v13, vcc, 0, v7, vcc
	global_load_dword v28, v[12:13], off nt
	v_add_co_u32_e32 v12, vcc, s1, v6
	s_mov_b32 s1, 0x1e000
	s_nop 0
	v_addc_co_u32_e32 v13, vcc, 0, v7, vcc
	global_load_dword v29, v[12:13], off nt
	v_add_co_u32_e32 v12, vcc, s1, v6
	s_mov_b32 s1, 0x20000
	s_nop 0
	v_addc_co_u32_e32 v13, vcc, 0, v7, vcc
	global_load_dword v30, v[12:13], off nt
	v_add_co_u32_e32 v12, vcc, s1, v6
	s_mov_b32 s1, 0x22000
	s_nop 0
	v_addc_co_u32_e32 v13, vcc, 0, v7, vcc
	global_load_dword v31, v[12:13], off nt
	v_add_co_u32_e32 v12, vcc, s1, v6
	s_mov_b32 s1, 0x24000
	s_nop 0
	v_addc_co_u32_e32 v13, vcc, 0, v7, vcc
	global_load_dword v32, v[12:13], off nt
	v_add_co_u32_e32 v12, vcc, s1, v6
	s_mov_b32 s1, 0x26000
	s_nop 0
	v_addc_co_u32_e32 v13, vcc, 0, v7, vcc
	global_load_dword v33, v[12:13], off nt
	v_add_co_u32_e32 v12, vcc, s1, v6
	s_mov_b32 s1, 0x28000
	s_nop 0
	v_addc_co_u32_e32 v13, vcc, 0, v7, vcc
	global_load_dword v34, v[12:13], off nt
	v_add_co_u32_e32 v12, vcc, s1, v6
	s_mov_b32 s1, 0x2a000
	s_nop 0
	v_addc_co_u32_e32 v13, vcc, 0, v7, vcc
	global_load_dword v35, v[12:13], off nt
	v_add_co_u32_e32 v12, vcc, s1, v6
	s_mov_b32 s1, 0x2c000
	s_nop 0
	v_addc_co_u32_e32 v13, vcc, 0, v7, vcc
	global_load_dword v36, v[12:13], off nt
	v_add_co_u32_e32 v12, vcc, s1, v6
	s_mov_b32 s1, 0x2e000
	s_nop 0
	v_addc_co_u32_e32 v13, vcc, 0, v7, vcc
	global_load_dword v37, v[12:13], off nt
	v_add_co_u32_e32 v12, vcc, s1, v6
	s_mov_b32 s1, 0x30000
	s_nop 0
	v_addc_co_u32_e32 v13, vcc, 0, v7, vcc
	global_load_dword v38, v[12:13], off nt
	v_add_co_u32_e32 v12, vcc, s1, v6
	s_mov_b32 s1, 0x32000
	s_nop 0
	v_addc_co_u32_e32 v13, vcc, 0, v7, vcc
	global_load_dword v39, v[12:13], off nt
	v_add_co_u32_e32 v12, vcc, s1, v6
	s_mov_b32 s1, 0x34000
	s_nop 0
	v_addc_co_u32_e32 v13, vcc, 0, v7, vcc
	global_load_dword v40, v[12:13], off nt
	v_add_co_u32_e32 v12, vcc, s1, v6
	s_mov_b32 s1, 0x36000
	s_nop 0
	v_addc_co_u32_e32 v13, vcc, 0, v7, vcc
	global_load_dword v41, v[12:13], off nt
	v_add_co_u32_e32 v12, vcc, s1, v6
	s_mov_b32 s1, 0x38000
	s_nop 0
	v_addc_co_u32_e32 v13, vcc, 0, v7, vcc
	global_load_dword v42, v[12:13], off nt
	v_add_co_u32_e32 v12, vcc, s1, v6
	s_mov_b32 s1, 0x3a000
	s_nop 0
	v_addc_co_u32_e32 v13, vcc, 0, v7, vcc
	global_load_dword v43, v[12:13], off nt
	v_add_co_u32_e32 v12, vcc, s1, v6
	s_mov_b32 s1, 0x3c000
	s_nop 0
	v_addc_co_u32_e32 v13, vcc, 0, v7, vcc
	global_load_dword v44, v[12:13], off nt
	v_add_co_u32_e32 v12, vcc, s1, v6
	s_mov_b32 s1, 0x3e000
	s_nop 0
	v_addc_co_u32_e32 v13, vcc, 0, v7, vcc
	v_add_co_u32_e32 v6, vcc, s1, v6
	global_load_dword v12, v[12:13], off nt
	s_nop 0
	v_addc_co_u32_e32 v7, vcc, 0, v7, vcc
	global_load_dword v6, v[6:7], off nt
	v_add_u32_e32 v7, 0x400, v3
	s_waitcnt vmcnt(30)
	ds_write2_b32 v3, v14, v16 offset1:66
	s_waitcnt vmcnt(28)
	ds_write2_b32 v3, v17, v18 offset0:132 offset1:198
	s_waitcnt vmcnt(26)
	ds_write2_b32 v7, v19, v20 offset0:8 offset1:74
	s_waitcnt vmcnt(24)
	ds_write2_b32 v7, v21, v22 offset0:140 offset1:206
	v_add_u32_e32 v7, 0x800, v3
	s_waitcnt vmcnt(22)
	ds_write2_b32 v7, v23, v24 offset0:16 offset1:82
	s_waitcnt vmcnt(20)
	ds_write2_b32 v7, v25, v26 offset0:148 offset1:214
	v_add_u32_e32 v7, 0xc00, v3
	s_waitcnt vmcnt(18)
	ds_write2_b32 v7, v27, v28 offset0:24 offset1:90
	s_waitcnt vmcnt(16)
	ds_write2_b32 v7, v29, v30 offset0:156 offset1:222
	v_add_u32_e32 v7, 0x1000, v3
	s_waitcnt vmcnt(14)
	ds_write2_b32 v7, v31, v32 offset0:32 offset1:98
	s_waitcnt vmcnt(12)
	ds_write2_b32 v7, v33, v34 offset0:164 offset1:230
	v_add_u32_e32 v7, 0x1400, v3
	s_waitcnt vmcnt(10)
	ds_write2_b32 v7, v35, v36 offset0:40 offset1:106
	s_waitcnt vmcnt(8)
	ds_write2_b32 v7, v37, v38 offset0:172 offset1:238
	v_add_u32_e32 v7, 0x1800, v3
	s_waitcnt vmcnt(6)
	ds_write2_b32 v7, v39, v40 offset0:48 offset1:114
	s_waitcnt vmcnt(4)
	ds_write2_b32 v7, v41, v42 offset0:180 offset1:246
	v_add_u32_e32 v7, 0x1c00, v3
	s_waitcnt vmcnt(2)
	ds_write2_b32 v7, v43, v44 offset0:56 offset1:122
	s_waitcnt vmcnt(0)
	ds_write2_b32 v7, v12, v6 offset0:188 offset1:254
	s_waitcnt lgkmcnt(0)
	ds_read2_b32 v[12:13], v8 offset0:33 offset1:41
	ds_read2_b32 v[20:21], v8 offset1:8
	s_lshl_b32 s1, s3, 1
	s_add_u32 s4, s15, s1
	s_addc_u32 s5, s18, 0
	v_lshlrev_b32_e32 v14, 1, v4
	ds_read2_b32 v[22:23], v8 offset0:66 offset1:74
	ds_read2_b32 v[24:25], v8 offset0:99 offset1:107
	v_lshl_add_u64 v[6:7], s[4:5], 0, v[14:15]
	s_waitcnt lgkmcnt(2)
	v_bfe_u32 v14, v20, 16, 1
	s_movk_i32 s1, 0x7fff
	v_readlane_b32 s69, v250, 24
	v_add3_u32 v14, v20, v14, s1
	v_bfe_u32 v16, v12, 16, 1
	s_mov_b32 s69, 0xffff0000
	v_lshrrev_b32_e32 v14, 16, v14
	v_add3_u32 v12, v12, v16, s1
	ds_read2_b32 v[26:27], v8 offset0:132 offset1:140
	ds_read2_b32 v[28:29], v8 offset0:165 offset1:173
	v_and_or_b32 v16, v12, s69, v14
	s_waitcnt lgkmcnt(3)
	v_bfe_u32 v12, v22, 16, 1
	v_add3_u32 v12, v22, v12, s1
	s_waitcnt lgkmcnt(2)
	v_bfe_u32 v14, v24, 16, 1
	v_lshrrev_b32_e32 v12, 16, v12
	v_add3_u32 v14, v24, v14, s1
	ds_read2_b32 v[30:31], v8 offset0:198 offset1:206
	ds_read2_b32 v[32:33], v8 offset0:231 offset1:239
	v_and_or_b32 v17, v14, s69, v12
	s_waitcnt lgkmcnt(3)
	v_bfe_u32 v12, v26, 16, 1
	v_add3_u32 v12, v26, v12, s1
	s_waitcnt lgkmcnt(2)
	v_bfe_u32 v14, v28, 16, 1
	v_lshrrev_b32_e32 v12, 16, v12
	v_add3_u32 v14, v28, v14, s1
	v_and_or_b32 v18, v14, s69, v12
	s_waitcnt lgkmcnt(1)
	v_bfe_u32 v12, v30, 16, 1
	v_add3_u32 v12, v30, v12, s1
	s_waitcnt lgkmcnt(0)
	v_bfe_u32 v14, v32, 16, 1
	v_lshrrev_b32_e32 v12, 16, v12
	v_add3_u32 v14, v32, v14, s1
	v_add_u32_e32 v34, s2, v5
	s_mov_b64 s[4:5], 0x900000
	v_and_or_b32 v19, v14, s69, v12
	v_ashrrev_i32_e32 v35, 31, v34
	v_bfe_u32 v12, v21, 16, 1
	v_lshl_add_u64 v[6:7], v[6:7], 0, s[4:5]
	v_lshlrev_b64 v[34:35], 11, v[34:35]
	v_add3_u32 v12, v21, v12, s1
	v_bfe_u32 v14, v13, 16, 1
	v_lshl_add_u64 v[34:35], v[6:7], 0, v[34:35]
	v_lshrrev_b32_e32 v12, 16, v12
	v_add3_u32 v13, v13, v14, s1
	global_store_dwordx4 v[34:35], v[16:19], off
	v_add_u32_e32 v34, s2, v10
	v_ashrrev_i32_e32 v35, 31, v34
	v_and_or_b32 v16, v13, s69, v12
	v_bfe_u32 v12, v23, 16, 1
	v_add3_u32 v12, v23, v12, s1
	v_bfe_u32 v13, v25, 16, 1
	v_lshrrev_b32_e32 v12, 16, v12
	v_add3_u32 v13, v25, v13, s1
	v_and_or_b32 v17, v13, s69, v12
	v_bfe_u32 v12, v27, 16, 1
	v_add3_u32 v12, v27, v12, s1
	v_bfe_u32 v13, v29, 16, 1
	v_lshrrev_b32_e32 v12, 16, v12
	v_add3_u32 v13, v29, v13, s1
	v_and_or_b32 v18, v13, s69, v12
	v_bfe_u32 v12, v31, 16, 1
	v_add3_u32 v12, v31, v12, s1
	v_bfe_u32 v13, v33, 16, 1
	v_lshrrev_b32_e32 v12, 16, v12
	v_add3_u32 v13, v33, v13, s1
	v_and_or_b32 v19, v13, s69, v12
	v_add_u32_e32 v12, s2, v9
	v_ashrrev_i32_e32 v13, 31, v12
	v_lshlrev_b64 v[12:13], 11, v[12:13]
	v_lshl_add_u64 v[12:13], v[6:7], 0, v[12:13]
	global_store_dwordx4 v[12:13], v[16:19], off
	ds_read2_b32 v[12:13], v8 offset0:49 offset1:57
	ds_read2_b32 v[20:21], v8 offset0:16 offset1:24
	ds_read2_b32 v[22:23], v8 offset0:82 offset1:90
	ds_read2_b32 v[24:25], v8 offset0:115 offset1:123
	ds_read2_b32 v[26:27], v8 offset0:148 offset1:156
	ds_read2_b32 v[28:29], v8 offset0:181 offset1:189
	ds_read2_b32 v[30:31], v8 offset0:214 offset1:222
	ds_read2_b32 v[32:33], v8 offset0:247 offset1:255
	s_waitcnt lgkmcnt(7)
	v_bfe_u32 v16, v12, 16, 1
	s_waitcnt lgkmcnt(6)
	v_bfe_u32 v14, v20, 16, 1
	v_add3_u32 v14, v20, v14, s1
	v_lshrrev_b32_e32 v14, 16, v14
	v_add3_u32 v12, v12, v16, s1
	v_and_or_b32 v16, v12, s69, v14
	s_waitcnt lgkmcnt(5)
	v_bfe_u32 v12, v22, 16, 1
	v_add3_u32 v12, v22, v12, s1
	s_waitcnt lgkmcnt(4)
	v_bfe_u32 v14, v24, 16, 1
	v_lshrrev_b32_e32 v12, 16, v12
	v_add3_u32 v14, v24, v14, s1
	v_and_or_b32 v17, v14, s69, v12
	s_waitcnt lgkmcnt(3)
	v_bfe_u32 v12, v26, 16, 1
	v_add3_u32 v12, v26, v12, s1
	s_waitcnt lgkmcnt(2)
	v_bfe_u32 v14, v28, 16, 1
	v_lshrrev_b32_e32 v12, 16, v12
	v_add3_u32 v14, v28, v14, s1
	v_and_or_b32 v18, v14, s69, v12
	s_waitcnt lgkmcnt(1)
	v_bfe_u32 v12, v30, 16, 1
	v_add3_u32 v12, v30, v12, s1
	s_waitcnt lgkmcnt(0)
	v_bfe_u32 v14, v32, 16, 1
	v_lshrrev_b32_e32 v12, 16, v12
	v_add3_u32 v14, v32, v14, s1
	v_and_or_b32 v19, v14, s69, v12
	v_bfe_u32 v12, v21, 16, 1
	v_lshlrev_b64 v[34:35], 11, v[34:35]
	v_add3_u32 v12, v21, v12, s1
	v_bfe_u32 v14, v13, 16, 1
	v_lshl_add_u64 v[34:35], v[6:7], 0, v[34:35]
	v_lshrrev_b32_e32 v12, 16, v12
	v_add3_u32 v13, v13, v14, s1
	global_store_dwordx4 v[34:35], v[16:19], off
	v_readlane_b32 s64, v250, 19
	v_readlane_b32 s65, v250, 20
	v_and_or_b32 v16, v13, s69, v12
	v_bfe_u32 v12, v23, 16, 1
	v_add3_u32 v12, v23, v12, s1
	v_bfe_u32 v13, v25, 16, 1
	v_lshrrev_b32_e32 v12, 16, v12
	v_add3_u32 v13, v25, v13, s1
	v_and_or_b32 v17, v13, s69, v12
	v_bfe_u32 v12, v27, 16, 1
	v_add3_u32 v12, v27, v12, s1
	v_bfe_u32 v13, v29, 16, 1
	v_lshrrev_b32_e32 v12, 16, v12
	v_add3_u32 v13, v29, v13, s1
	v_and_or_b32 v18, v13, s69, v12
	v_bfe_u32 v12, v31, 16, 1
	v_add3_u32 v12, v31, v12, s1
	v_bfe_u32 v13, v33, 16, 1
	v_lshrrev_b32_e32 v12, 16, v12
	v_add3_u32 v13, v33, v13, s1
	v_and_or_b32 v19, v13, s69, v12
	v_add_u32_e32 v12, s2, v11
	v_ashrrev_i32_e32 v13, 31, v12
	v_lshlrev_b64 v[12:13], 11, v[12:13]
	v_lshl_add_u64 v[6:7], v[6:7], 0, v[12:13]
	global_store_dwordx4 v[6:7], v[16:19], off
	s_waitcnt lgkmcnt(0)
	v_readlane_b32 s70, v250, 25
	v_readlane_b32 s71, v250, 26
	v_readlane_b32 s61, v250, 16
	v_readlane_b32 s72, v250, 27
	v_readlane_b32 s73, v250, 28
	v_readlane_b32 s70, v251, 28
	v_readlane_b32 s64, v255, 17
	v_readlane_b32 s74, v255, 2
	v_readlane_b32 s71, v251, 29
	v_readlane_b32 s65, v255, 18
	v_readlane_b32 s61, v255, 16
	s_movk_i32 s60, 0x2c00
	s_movk_i32 s73, 0x1600
	s_movk_i32 s72, 0x80
	v_readlane_b32 s75, v255, 3
	v_readlane_b32 s62, v250, 17
	v_readlane_b32 s63, v250, 18
